# compressed-attention pass 2: K/V fragments of the next 32-key group are fetched into spare registers while the current group is computed (was load-then-wait every group)
# baseline (speedup 1.0000x reference)
.LBB0_1424:
	v_mov_b32_e32 v47, 0
	s_andn2_b64 vcc, exec, s[8:9]
	v_mov_b32_e32 v46, v47
	v_mov_b32_e32 v45, v47
	v_mov_b32_e32 v44, v47
	v_mov_b32_e32 v51, v47
	v_mov_b32_e32 v50, v47
	v_mov_b32_e32 v49, v47
	v_mov_b32_e32 v48, v47
	s_waitcnt vmcnt(0)
	v_mov_b32_e32 v55, v47
	v_mov_b32_e32 v54, v47
	v_mov_b32_e32 v53, v47
	v_mov_b32_e32 v52, v47
	v_mov_b32_e32 v59, v47
	v_mov_b32_e32 v58, v47
	v_mov_b32_e32 v57, v47
	v_mov_b32_e32 v56, v47
	v_mov_b32_e32 v63, v47
	v_mov_b32_e32 v62, v47
	v_mov_b32_e32 v61, v47
	v_mov_b32_e32 v60, v47
	v_mov_b32_e32 v67, v47
	v_mov_b32_e32 v66, v47
	v_mov_b32_e32 v65, v47
	v_mov_b32_e32 v64, v47
	v_mov_b32_e32 v71, v47
	v_mov_b32_e32 v70, v47
	v_mov_b32_e32 v69, v47
	v_mov_b32_e32 v68, v47
	v_mov_b32_e32 v75, v47
	v_mov_b32_e32 v74, v47
	v_mov_b32_e32 v73, v47
	v_mov_b32_e32 v72, v47
	v_mov_b32_e32 v79, v47
	v_mov_b32_e32 v78, v47
	v_mov_b32_e32 v77, v47
	v_mov_b32_e32 v76, v47
	v_mov_b32_e32 v83, v47
	v_mov_b32_e32 v82, v47
	v_mov_b32_e32 v81, v47
	v_mov_b32_e32 v80, v47
	v_mov_b32_e32 v87, v47
	v_mov_b32_e32 v86, v47
	v_mov_b32_e32 v85, v47
	v_mov_b32_e32 v84, v47
	v_mov_b32_e32 v91, v47
	v_mov_b32_e32 v90, v47
	v_mov_b32_e32 v89, v47
	v_mov_b32_e32 v88, v47
	v_mov_b32_e32 v95, v47
	v_mov_b32_e32 v94, v47
	v_mov_b32_e32 v93, v47
	v_mov_b32_e32 v92, v47
	v_mov_b32_e32 v103, v47
	v_mov_b32_e32 v102, v47
	v_mov_b32_e32 v101, v47
	v_mov_b32_e32 v100, v47
	v_mov_b32_e32 v107, v47
	v_mov_b32_e32 v106, v47
	v_mov_b32_e32 v105, v47
	v_mov_b32_e32 v104, v47
	v_mov_b32_e32 v99, v47
	v_mov_b32_e32 v98, v47
	v_mov_b32_e32 v97, v47
	v_mov_b32_e32 v96, v47
	s_cbranch_vccnz .LBB0_1509
	v_log_f32_e32 v3, v3
	v_log_f32_e32 v2, v2
	v_log_f32_e32 v5, v5
	v_log_f32_e32 v4, v4
	s_add_i32 s10, s97, 0xfffffdf1
	s_not_b32 s6, s12
	v_readlane_b32 s4, v243, 60
	v_add_f32_e32 v168, v3, v113
	v_add_f32_e32 v169, v2, v114
	v_lshl_add_u32 v2, v110, 10, s18
	v_lshlrev_b32_e32 v3, 2, v10
	s_add_u32 s4, s90, s4
	v_add3_u32 v170, v2, v3, 0
	v_lshlrev_b32_e32 v2, 6, v10
	s_addc_u32 s5, s91, 0
	v_mov_b32_e32 v96, 0
	v_add_f32_e32 v166, v5, v111
	v_add_f32_e32 v167, v4, v112
	v_mov_b32_e32 v156, v148
	v_mov_b32_e32 v157, v148
	v_mov_b32_e32 v158, v152
	v_mov_b32_e32 v159, v152
	v_mov_b32_e32 v160, v150
	v_mov_b32_e32 v161, v150
	v_mov_b32_e32 v162, v154
	v_mov_b32_e32 v163, v154
	v_sub_u32_e32 v171, v110, v2
	v_lshl_add_u64 v[164:165], v[108:109], 1, s[4:5]
	v_mov_b32_e32 v172, s6
	v_mov_b32_e32 v97, v96
	v_mov_b32_e32 v98, v96
	v_mov_b32_e32 v99, v96
	v_mov_b32_e32 v104, v96
	v_mov_b32_e32 v105, v96
	v_mov_b32_e32 v106, v96
	v_mov_b32_e32 v107, v96
	v_mov_b32_e32 v100, v96
	v_mov_b32_e32 v101, v96
	v_mov_b32_e32 v102, v96
	v_mov_b32_e32 v103, v96
	v_mov_b32_e32 v92, v96
	v_mov_b32_e32 v93, v96
	v_mov_b32_e32 v94, v96
	v_mov_b32_e32 v95, v96
	v_mov_b32_e32 v88, v96
	v_mov_b32_e32 v89, v96
	v_mov_b32_e32 v90, v96
	v_mov_b32_e32 v91, v96
	v_mov_b32_e32 v84, v96
	v_mov_b32_e32 v85, v96
	v_mov_b32_e32 v86, v96
	v_mov_b32_e32 v87, v96
	v_mov_b32_e32 v80, v96
	v_mov_b32_e32 v81, v96
	v_mov_b32_e32 v82, v96
	v_mov_b32_e32 v83, v96
	v_mov_b32_e32 v76, v96
	v_mov_b32_e32 v77, v96
	v_mov_b32_e32 v78, v96
	v_mov_b32_e32 v79, v96
	v_mov_b32_e32 v72, v96
	v_mov_b32_e32 v73, v96
	v_mov_b32_e32 v74, v96
	v_mov_b32_e32 v75, v96
	v_mov_b32_e32 v68, v96
	v_mov_b32_e32 v69, v96
	v_mov_b32_e32 v70, v96
	v_mov_b32_e32 v71, v96
	v_mov_b32_e32 v64, v96
	v_mov_b32_e32 v65, v96
	v_mov_b32_e32 v66, v96
	v_mov_b32_e32 v67, v96
	v_mov_b32_e32 v60, v96
	v_mov_b32_e32 v61, v96
	v_mov_b32_e32 v62, v96
	v_mov_b32_e32 v63, v96
	v_mov_b32_e32 v56, v96
	v_mov_b32_e32 v57, v96
	v_mov_b32_e32 v58, v96
	v_mov_b32_e32 v59, v96
	v_mov_b32_e32 v52, v96
	v_mov_b32_e32 v53, v96
	v_mov_b32_e32 v54, v96
	v_mov_b32_e32 v55, v96
	v_mov_b32_e32 v48, v96
	v_mov_b32_e32 v49, v96
	v_mov_b32_e32 v50, v96
	v_mov_b32_e32 v51, v96
	v_mov_b32_e32 v44, v96
	v_mov_b32_e32 v45, v96
	v_mov_b32_e32 v46, v96
	v_mov_b32_e32 v47, v96
	v_add_co_u32_e32 v6, vcc, s80, v164
	v_addc_co_u32_e32 v7, vcc, -1, v165, vcc
	global_load_dwordx4 v[196:199], v[6:7], off offset:-3072
	global_load_dwordx4 v[214:217], v[6:7], off offset:-1024
	global_load_dwordx4 v[224:227], v[6:7], off offset:-2048
	global_load_dwordx4 v[228:231], v[6:7], off offset:0
	global_load_dwordx4 v[244:247], v[164:165], off offset:-3072
	global_load_dwordx4 v[248:251], v[164:165], off offset:-2048
	global_load_dwordx4 v[252:255], v[164:165], off offset:-1024
	global_load_dwordx2 v[218:219], v[164:165], off offset:0
	global_load_dword v220, v[164:165], off offset:8
	global_load_dword v223, v[164:165], off offset:12
	v_lshl_add_u64 v[164:165], v[164:165], 0, s[58:59]
	s_branch .LBB0_1427

.LBB0_1427:
	s_waitcnt vmcnt(0)
	v_mov_b64_e32 v[124:125], v[196:197]
	v_mov_b64_e32 v[126:127], v[198:199]
	v_mov_b64_e32 v[128:129], v[214:215]
	v_mov_b64_e32 v[130:131], v[216:217]
	v_mov_b64_e32 v[132:133], v[224:225]
	v_mov_b64_e32 v[134:135], v[226:227]
	v_mov_b64_e32 v[136:137], v[228:229]
	v_mov_b64_e32 v[138:139], v[230:231]
	v_mov_b64_e32 v[120:121], v[244:245]
	v_mov_b64_e32 v[122:123], v[246:247]
	v_mov_b64_e32 v[116:117], v[248:249]
	v_mov_b64_e32 v[118:119], v[250:251]
	v_mov_b64_e32 v[112:113], v[252:253]
	v_mov_b64_e32 v[114:115], v[254:255]
	v_mov_b64_e32 v[108:109], v[218:219]
	v_mov_b32_e32 v110, v220
	v_mov_b32_e32 v111, v223
	v_add_co_u32_e32 v6, vcc, s80, v164
	s_cmpk_lt_i32 s10, 0x7f
	s_nop 0
	v_addc_co_u32_e32 v7, vcc, -1, v165, vcc
	global_load_dwordx4 v[196:199], v[6:7], off offset:-3072
	global_load_dwordx4 v[214:217], v[6:7], off offset:-1024
	global_load_dwordx4 v[224:227], v[6:7], off offset:-2048
	global_load_dwordx4 v[228:231], v[6:7], off offset:0
	global_load_dwordx4 v[244:247], v[164:165], off offset:-3072
	global_load_dwordx4 v[248:251], v[164:165], off offset:-2048
	global_load_dwordx4 v[252:255], v[164:165], off offset:-1024
	global_load_dwordx2 v[218:219], v[164:165], off offset:0
	global_load_dword v220, v[164:165], off offset:8
	global_load_dword v223, v[164:165], off offset:12
	s_cselect_b64 s[8:9], -1, 0
	s_cmpk_gt_i32 s10, 0x7e
	s_mov_b64 s[6:7], -1
	v_mfma_f32_16x16x32_bf16 v[2:5], v[124:127], v[12:15], 0
	v_mfma_f32_16x16x32_bf16 v[6:9], v[128:131], v[12:15], 0
	v_mfma_f32_16x16x32_bf16 v[140:143], v[132:135], v[16:19], v[2:5]
	v_mfma_f32_16x16x32_bf16 v[144:147], v[136:139], v[16:19], v[6:9]
	s_cbranch_scc1 .LBB0_1445
	v_add_u32_e32 v149, s10, v171
	v_add_u32_e32 v4, 0x1f0, v149
	v_cmp_lt_i32_e32 vcc, -1, v4
	v_mov_b32_e32 v3, 0xff800000
	v_mov_b32_e32 v2, 0xff800000
	s_and_saveexec_b64 s[6:7], vcc
	s_cbranch_execz .LBB0_1430
	v_min_u32_e32 v2, 0x7f, v4
	v_lshl_add_u32 v2, v2, 2, s87
	ds_read_b32 v2, v2
	s_waitcnt lgkmcnt(0)
	v_add_f32_e32 v2, v140, v2
	v_mul_f32_e32 v2, 0x3fb8aa3b, v2

.LBB0_1447:
	v_sub_f32_e32 v2, v2, v166
	v_exp_f32_e32 v173, v2
	v_sub_f32_e32 v2, v3, v166
	v_exp_f32_e32 v184, v2
	v_sub_f32_e32 v2, v4, v166
	v_exp_f32_e32 v183, v2
	v_sub_f32_e32 v2, v5, v166
	v_exp_f32_e32 v182, v2
	v_sub_f32_e32 v2, v6, v166
	v_exp_f32_e32 v185, v2
	v_sub_f32_e32 v2, v7, v166
	v_exp_f32_e32 v187, v2
	v_sub_f32_e32 v2, v8, v166
	v_exp_f32_e32 v186, v2
	v_sub_f32_e32 v2, v9, v166
	v_exp_f32_e32 v149, v2
	v_cvt_pk_bf16_f32 v2, v173, v184
	v_cvt_pk_bf16_f32 v3, v183, v182
	v_cvt_pk_bf16_f32 v4, v185, v187
	v_cvt_pk_bf16_f32 v5, v186, v149
	v_cndmask_b32_e64 v6, 0, 1, s[8:9]
	v_mfma_f32_16x16x32_bf16 v[96:99], v[120:123], v[2:5], v[96:99]
	v_cmp_ne_u32_e64 s[6:7], 1, v6
	s_andn2_b64 vcc, exec, s[8:9]
	s_mov_b64 s[8:9], -1
	v_mfma_f32_16x16x32_bf16 v[104:107], v[116:119], v[2:5], v[104:107]
	v_mfma_f32_16x16x32_bf16 v[100:103], v[112:115], v[2:5], v[100:103]
	v_mfma_f32_16x16x32_bf16 v[92:95], v[108:111], v[2:5], v[92:95]
	v_mfma_f32_16x16x32_bf16 v[2:5], v[124:127], v[20:23], 0
	v_mfma_f32_16x16x32_bf16 v[140:143], v[132:135], v[24:27], v[2:5]
	v_mfma_f32_16x16x32_bf16 v[2:5], v[128:131], v[20:23], 0
	v_mfma_f32_16x16x32_bf16 v[144:147], v[136:139], v[24:27], v[2:5]
	s_cbranch_vccnz .LBB0_1465
	v_add_u32_e32 v151, s10, v171
	s_nop 4
	v_add_u32_e32 v4, 0x1f0, v151
	v_cmp_lt_i32_e32 vcc, -1, v4
	v_mov_b32_e32 v3, 0xff800000
	v_mov_b32_e32 v2, 0xff800000
	s_and_saveexec_b64 s[8:9], vcc
	s_cbranch_execz .LBB0_1450
	v_min_u32_e32 v2, 0x7f, v4
	v_lshl_add_u32 v2, v2, 2, s87
	ds_read_b32 v2, v2 offset:512
	s_waitcnt lgkmcnt(0)
	v_add_f32_e32 v2, v140, v2
	v_mul_f32_e32 v2, 0x3fb8aa3b, v2

.LBB0_1509:
	s_waitcnt vmcnt(0)
	s_ashr_i32 s5, s97, 6
	s_cmp_gt_i32 s5, 0
	s_cselect_b64 s[12:13], -1, 0
	s_and_b64 s[6:7], s[12:13], exec
	s_cselect_b32 s4, 2, 1
	s_cmp_gt_i32 s5, 1
	s_cselect_b64 s[10:11], -1, 0
	s_cmp_lg_u64 s[10:11], 0
	s_waitcnt lgkmcnt(0)
	s_addc_u32 s4, s4, 0
	s_add_i32 s21, s5, -2
	s_sub_i32 s6, 16, s4
	s_max_i32 s7, s21, 0
	s_min_u32 s23, s6, s7
	v_cmp_gt_u32_e64 s[8:9], 16, v181
	s_and_saveexec_b64 s[6:7], s[8:9]
	s_cbranch_execz .LBB0_1515
	v_lshl_add_u32 v2, v181, 6, s96
	s_andn2_b64 vcc, exec, s[12:13]
	ds_write_b32 v2, v11 offset:16384
	s_cbranch_vccnz .LBB0_1512
	v_mov_b32_e32 v3, s5
	ds_write_b32 v2, v3 offset:16388

.LBB0_1924:
	v_mov_b32_e32 v47, 0
	s_andn2_b64 vcc, exec, s[14:15]
	v_mov_b32_e32 v46, v47
	v_mov_b32_e32 v45, v47
	v_mov_b32_e32 v44, v47
	v_mov_b32_e32 v51, v47
	v_mov_b32_e32 v50, v47
	v_mov_b32_e32 v49, v47
	v_mov_b32_e32 v48, v47
	s_waitcnt vmcnt(0)
	v_mov_b32_e32 v55, v47
	v_mov_b32_e32 v54, v47
	v_mov_b32_e32 v53, v47
	v_mov_b32_e32 v52, v47
	v_mov_b32_e32 v59, v47
	v_mov_b32_e32 v58, v47
	v_mov_b32_e32 v57, v47
	v_mov_b32_e32 v56, v47
	v_mov_b32_e32 v63, v47
	v_mov_b32_e32 v62, v47
	v_mov_b32_e32 v61, v47
	v_mov_b32_e32 v60, v47
	v_mov_b32_e32 v67, v47
	v_mov_b32_e32 v66, v47
	v_mov_b32_e32 v65, v47
	v_mov_b32_e32 v64, v47
	v_mov_b32_e32 v71, v47
	v_mov_b32_e32 v70, v47
	v_mov_b32_e32 v69, v47
	v_mov_b32_e32 v68, v47
	v_mov_b32_e32 v75, v47
	v_mov_b32_e32 v74, v47
	v_mov_b32_e32 v73, v47
	v_mov_b32_e32 v72, v47
	v_mov_b32_e32 v79, v47
	v_mov_b32_e32 v78, v47
	v_mov_b32_e32 v77, v47
	v_mov_b32_e32 v76, v47
	v_mov_b32_e32 v83, v47
	v_mov_b32_e32 v82, v47
	v_mov_b32_e32 v81, v47
	v_mov_b32_e32 v80, v47
	v_mov_b32_e32 v87, v47
	v_mov_b32_e32 v86, v47
	v_mov_b32_e32 v85, v47
	v_mov_b32_e32 v84, v47
	v_mov_b32_e32 v91, v47
	v_mov_b32_e32 v90, v47
	v_mov_b32_e32 v89, v47
	v_mov_b32_e32 v88, v47
	v_mov_b32_e32 v95, v47
	v_mov_b32_e32 v94, v47
	v_mov_b32_e32 v93, v47
	v_mov_b32_e32 v92, v47
	v_mov_b32_e32 v103, v47
	v_mov_b32_e32 v102, v47
	v_mov_b32_e32 v101, v47
	v_mov_b32_e32 v100, v47
	v_mov_b32_e32 v107, v47
	v_mov_b32_e32 v106, v47
	v_mov_b32_e32 v105, v47
	v_mov_b32_e32 v104, v47
	v_mov_b32_e32 v99, v47
	v_mov_b32_e32 v98, v47
	v_mov_b32_e32 v97, v47
	v_mov_b32_e32 v96, v47
	s_cbranch_vccnz .LBB0_2009
	v_log_f32_e32 v3, v3
	v_log_f32_e32 v2, v2
	v_log_f32_e32 v5, v5
	v_log_f32_e32 v4, v4
	s_add_i32 s23, s35, 0x3d71
	s_not_b32 s12, s21
	v_readlane_b32 s4, v243, 60
	v_add_f32_e32 v168, v3, v113
	v_add_f32_e32 v169, v2, v114
	v_lshl_add_u32 v2, v110, 10, s29
	v_lshlrev_b32_e32 v3, 2, v10
	s_add_u32 s4, s16, s4
	v_add3_u32 v170, v2, v3, 0
	v_lshlrev_b32_e32 v2, 6, v10
	s_addc_u32 s5, s17, 0
	v_mov_b32_e32 v96, 0
	v_add_f32_e32 v166, v5, v111
	v_add_f32_e32 v167, v4, v112
	v_mov_b32_e32 v156, v148
	v_mov_b32_e32 v157, v148
	v_mov_b32_e32 v158, v152
	v_mov_b32_e32 v159, v152
	v_mov_b32_e32 v160, v150
	v_mov_b32_e32 v161, v150
	v_mov_b32_e32 v162, v154
	v_mov_b32_e32 v163, v154
	v_sub_u32_e32 v171, v110, v2
	v_lshl_add_u64 v[164:165], v[108:109], 1, s[4:5]
	v_mov_b32_e32 v172, s12
	v_mov_b32_e32 v97, v96
	v_mov_b32_e32 v98, v96
	v_mov_b32_e32 v99, v96
	v_mov_b32_e32 v104, v96
	v_mov_b32_e32 v105, v96
	v_mov_b32_e32 v106, v96
	v_mov_b32_e32 v107, v96
	v_mov_b32_e32 v100, v96
	v_mov_b32_e32 v101, v96
	v_mov_b32_e32 v102, v96
	v_mov_b32_e32 v103, v96
	v_mov_b32_e32 v92, v96
	v_mov_b32_e32 v93, v96
	v_mov_b32_e32 v94, v96
	v_mov_b32_e32 v95, v96
	v_mov_b32_e32 v88, v96
	v_mov_b32_e32 v89, v96
	v_mov_b32_e32 v90, v96
	v_mov_b32_e32 v91, v96
	v_mov_b32_e32 v84, v96
	v_mov_b32_e32 v85, v96
	v_mov_b32_e32 v86, v96
	v_mov_b32_e32 v87, v96
	v_mov_b32_e32 v80, v96
	v_mov_b32_e32 v81, v96
	v_mov_b32_e32 v82, v96
	v_mov_b32_e32 v83, v96
	v_mov_b32_e32 v76, v96
	v_mov_b32_e32 v77, v96
	v_mov_b32_e32 v78, v96
	v_mov_b32_e32 v79, v96
	v_mov_b32_e32 v72, v96
	v_mov_b32_e32 v73, v96
	v_mov_b32_e32 v74, v96
	v_mov_b32_e32 v75, v96
	v_mov_b32_e32 v68, v96
	v_mov_b32_e32 v69, v96
	v_mov_b32_e32 v70, v96
	v_mov_b32_e32 v71, v96
	v_mov_b32_e32 v64, v96
	v_mov_b32_e32 v65, v96
	v_mov_b32_e32 v66, v96
	v_mov_b32_e32 v67, v96
	v_mov_b32_e32 v60, v96
	v_mov_b32_e32 v61, v96
	v_mov_b32_e32 v62, v96
	v_mov_b32_e32 v63, v96
	v_mov_b32_e32 v56, v96
	v_mov_b32_e32 v57, v96
	v_mov_b32_e32 v58, v96
	v_mov_b32_e32 v59, v96
	v_mov_b32_e32 v52, v96
	v_mov_b32_e32 v53, v96
	v_mov_b32_e32 v54, v96
	v_mov_b32_e32 v55, v96
	v_mov_b32_e32 v48, v96
	v_mov_b32_e32 v49, v96
	v_mov_b32_e32 v50, v96
	v_mov_b32_e32 v51, v96
	v_mov_b32_e32 v44, v96
	v_mov_b32_e32 v45, v96
	v_mov_b32_e32 v46, v96
	v_mov_b32_e32 v47, v96
	v_add_co_u32_e32 v6, vcc, s80, v164
	v_addc_co_u32_e32 v7, vcc, -1, v165, vcc
	global_load_dwordx4 v[196:199], v[6:7], off offset:-3072
	global_load_dwordx4 v[232:235], v[6:7], off offset:-1024
	global_load_dwordx4 v[244:247], v[6:7], off offset:-2048
	global_load_dwordx4 v[248:251], v[6:7], off offset:0
	global_load_dwordx4 v[252:255], v[164:165], off offset:-3072
	global_load_dwordx2 v[228:229], v[164:165], off offset:-2048
	global_load_dwordx2 v[236:237], v[164:165], off offset:-2040
	global_load_dword v195, v[164:165], off offset:-1024
	global_load_dword v200, v[164:165], off offset:-1020
	global_load_dword v203, v[164:165], off offset:-1016
	global_load_dword v221, v[164:165], off offset:-1012
	global_load_dword v222, v[164:165], off offset:0
	global_load_dword v231, v[164:165], off offset:4
	global_load_dword v239, v[164:165], off offset:8
	global_load_dword v240, v[164:165], off offset:12
	v_lshl_add_u64 v[164:165], v[164:165], 0, s[58:59]
	s_branch .LBB0_1927

.LBB0_1927:
	s_waitcnt vmcnt(0)
	v_mov_b64_e32 v[124:125], v[196:197]
	v_mov_b64_e32 v[126:127], v[198:199]
	v_mov_b64_e32 v[128:129], v[232:233]
	v_mov_b64_e32 v[130:131], v[234:235]
	v_mov_b64_e32 v[132:133], v[244:245]
	v_mov_b64_e32 v[134:135], v[246:247]
	v_mov_b64_e32 v[136:137], v[248:249]
	v_mov_b64_e32 v[138:139], v[250:251]
	v_mov_b64_e32 v[120:121], v[252:253]
	v_mov_b64_e32 v[122:123], v[254:255]
	v_mov_b64_e32 v[116:117], v[228:229]
	v_mov_b64_e32 v[118:119], v[236:237]
	v_mov_b32_e32 v112, v195
	v_mov_b32_e32 v113, v200
	v_mov_b32_e32 v114, v203
	v_mov_b32_e32 v115, v221
	v_mov_b32_e32 v108, v222
	v_mov_b32_e32 v109, v231
	v_mov_b32_e32 v110, v239
	v_mov_b32_e32 v111, v240
	v_add_co_u32_e32 v6, vcc, s80, v164
	s_cmpk_lt_i32 s23, 0x7f
	s_nop 0
	v_addc_co_u32_e32 v7, vcc, -1, v165, vcc
	global_load_dwordx4 v[196:199], v[6:7], off offset:-3072
	global_load_dwordx4 v[232:235], v[6:7], off offset:-1024
	global_load_dwordx4 v[244:247], v[6:7], off offset:-2048
	global_load_dwordx4 v[248:251], v[6:7], off offset:0
	global_load_dwordx4 v[252:255], v[164:165], off offset:-3072
	global_load_dwordx2 v[228:229], v[164:165], off offset:-2048
	global_load_dwordx2 v[236:237], v[164:165], off offset:-2040
	global_load_dword v195, v[164:165], off offset:-1024
	global_load_dword v200, v[164:165], off offset:-1020
	global_load_dword v203, v[164:165], off offset:-1016
	global_load_dword v221, v[164:165], off offset:-1012
	global_load_dword v222, v[164:165], off offset:0
	global_load_dword v231, v[164:165], off offset:4
	global_load_dword v239, v[164:165], off offset:8
	global_load_dword v240, v[164:165], off offset:12
	s_cselect_b64 s[14:15], -1, 0
	s_cmpk_gt_i32 s23, 0x7e
	s_mov_b64 s[12:13], -1
	v_mfma_f32_16x16x32_bf16 v[2:5], v[124:127], v[12:15], 0
	v_mfma_f32_16x16x32_bf16 v[6:9], v[128:131], v[12:15], 0
	v_mfma_f32_16x16x32_bf16 v[140:143], v[132:135], v[16:19], v[2:5]
	v_mfma_f32_16x16x32_bf16 v[144:147], v[136:139], v[16:19], v[6:9]
	s_cbranch_scc1 .LBB0_1945
	v_add_u32_e32 v149, s23, v171
	v_add_u32_e32 v4, 0x1f0, v149
	v_cmp_lt_i32_e32 vcc, -1, v4
	v_mov_b32_e32 v3, 0xff800000
	v_mov_b32_e32 v2, 0xff800000
	s_and_saveexec_b64 s[12:13], vcc
	s_cbranch_execz .LBB0_1930
	v_min_u32_e32 v2, 0x7f, v4
	v_lshl_add_u32 v2, v2, 2, s87
	ds_read_b32 v2, v2
	s_waitcnt lgkmcnt(0)
	v_add_f32_e32 v2, v140, v2
	v_mul_f32_e32 v2, 0x3fb8aa3b, v2

.LBB0_1947:
	v_sub_f32_e32 v2, v2, v166
	v_exp_f32_e32 v173, v2
	v_sub_f32_e32 v2, v3, v166
	v_exp_f32_e32 v184, v2
	v_sub_f32_e32 v2, v4, v166
	v_exp_f32_e32 v183, v2
	v_sub_f32_e32 v2, v5, v166
	v_exp_f32_e32 v182, v2
	v_sub_f32_e32 v2, v6, v166
	v_exp_f32_e32 v185, v2
	v_sub_f32_e32 v2, v7, v166
	v_exp_f32_e32 v187, v2
	v_sub_f32_e32 v2, v8, v166
	v_exp_f32_e32 v186, v2
	v_sub_f32_e32 v2, v9, v166
	v_exp_f32_e32 v149, v2
	v_cvt_pk_bf16_f32 v2, v173, v184
	v_cvt_pk_bf16_f32 v3, v183, v182
	v_cvt_pk_bf16_f32 v4, v185, v187
	v_cvt_pk_bf16_f32 v5, v186, v149
	v_cndmask_b32_e64 v6, 0, 1, s[14:15]
	v_mfma_f32_16x16x32_bf16 v[96:99], v[120:123], v[2:5], v[96:99]
	v_cmp_ne_u32_e64 s[12:13], 1, v6
	s_andn2_b64 vcc, exec, s[14:15]
	s_mov_b64 s[14:15], -1
	v_mfma_f32_16x16x32_bf16 v[104:107], v[116:119], v[2:5], v[104:107]
	v_mfma_f32_16x16x32_bf16 v[100:103], v[112:115], v[2:5], v[100:103]
	v_mfma_f32_16x16x32_bf16 v[92:95], v[108:111], v[2:5], v[92:95]
	v_mfma_f32_16x16x32_bf16 v[2:5], v[124:127], v[20:23], 0
	v_mfma_f32_16x16x32_bf16 v[140:143], v[132:135], v[24:27], v[2:5]
	v_mfma_f32_16x16x32_bf16 v[2:5], v[128:131], v[20:23], 0
	v_mfma_f32_16x16x32_bf16 v[144:147], v[136:139], v[24:27], v[2:5]
	s_cbranch_vccnz .LBB0_1965
	v_add_u32_e32 v151, s23, v171
	s_nop 4
	v_add_u32_e32 v4, 0x1f0, v151
	v_cmp_lt_i32_e32 vcc, -1, v4
	v_mov_b32_e32 v3, 0xff800000
	v_mov_b32_e32 v2, 0xff800000
	s_and_saveexec_b64 s[14:15], vcc
	s_cbranch_execz .LBB0_1950
	v_min_u32_e32 v2, 0x7f, v4
	v_lshl_add_u32 v2, v2, 2, s87
	ds_read_b32 v2, v2 offset:512
	s_waitcnt lgkmcnt(0)
	v_add_f32_e32 v2, v140, v2
	v_mul_f32_e32 v2, 0x3fb8aa3b, v2

.LBB0_2009:
	s_waitcnt vmcnt(0)
	s_ashr_i32 s5, s47, 6
	s_cmp_gt_i32 s5, 0
	s_cselect_b64 s[30:31], -1, 0
	s_and_b64 s[12:13], s[30:31], exec
	s_cselect_b32 s4, 2, 1
	s_cmp_gt_i32 s5, 1
	s_cselect_b64 s[14:15], -1, 0
	s_cmp_lg_u64 s[14:15], 0
	s_waitcnt lgkmcnt(0)
	s_addc_u32 s4, s4, 0
	s_add_i32 s21, s5, -2
	s_sub_i32 s12, 16, s4
	s_max_i32 s13, s21, 0
	s_min_u32 s23, s12, s13
	s_and_saveexec_b64 s[12:13], s[8:9]
	s_cbranch_execz .LBB0_2015
	v_lshl_add_u32 v2, v181, 6, s46
	s_andn2_b64 vcc, exec, s[30:31]
	ds_write_b32 v2, v11 offset:16384
	s_cbranch_vccnz .LBB0_2012
	v_mov_b32_e32 v3, s5
	ds_write_b32 v2, v3 offset:16388
